# MoBA PV step: P reads issued first in k-step order with progressive lgkmcnt waits so the MFMA chain starts on P[0]
# baseline (speedup 1.0000x reference)
; #define LAS __attribute__((address_space(3)))
; #define MFMA16(a, b, c) __builtin_amdgcn_mfma_f32_16x16x32_bf16((a), (b), (c), 0, 0, 0)
;     ...
;           for (int s0 = 0; s0 < ntile; s0 += 2, ++stepc) {
;             const LAS unsigned char* pbuf = Pb + (stepc & 1) * 16384;
;             const int tile = s0 + ptt;
;             if (tile < ntile && !(mode & 8)) {
;               const int rem = n - tile * 16;
;               const bool qv = fr < rem;
;               const int qidx = own ? tile * 16 + fr : (int)list[j * 256 + tile * 16 + (qv ? fr : 0)];
;               u32x4 pw[8];
; #pragma unroll
;               for (int ks = 0; ks < 8; ++ks) pw[ks] = *(const LAS u32x4*)(pbuf + ptt * 8192 + ks * 1024 + lane * 16);
;               LAS f32x4* op0 = (LAS f32x4*)(oacc + mo_oidx(qidx, dh * 8 + fq)); LAS f32x4* op1 = (LAS f32x4*)(oacc + mo_oidx(qidx, dh * 8 + 4 + fq));
;               const f32x4 a0 = *op0, a1 = *op1; const float al = lsl[qidx];
;               __builtin_amdgcn_sched_barrier(0);
;               f32x4 o0 = {0.f, 0.f, 0.f, 0.f}, o1 = {0.f, 0.f, 0.f, 0.f}, ol = {0.f, 0.f, 0.f, 0.f};
;               const bf16x8 ones = {0x3F80, 0x3F80, 0x3F80, 0x3F80, 0x3F80, 0x3F80, 0x3F80, 0x3F80};
; #pragma unroll
;               for (int ks = 0; ks < 8; ++ks) {
;                 const bf16x8 pb = __builtin_bit_cast(bf16x8, pw[ks]);
;                 o0 = MFMA16(vf[0][ks], pb, o0); o1 = MFMA16(vf[1][ks], pb, o1);
;                 if (dh == 0) ol = MFMA16(ones, pb, ol);
;               }
;               if (qv) {
;                 *op0 = a0 + o0; *op1 = a1 + o1;
;                 if (dh == 0 && fq == 0) lsl[qidx] = al + ol[0];
;               }
;             }
.LBB0_601:
	s_cmp_ge_i32 s74, s30
	s_cbranch_scc1 .LBB0_600
	v_cmp_gt_i32_e64 s[14:15], s57, v193
	s_and_b32 s16, s39, 0x4000
	v_add_u32_e32 v2, s16, v206
	v_cndmask_b32_e64 v1, 0, v193, s[14:15]
	v_add_u32_e32 v1, s79, v1
	ds_read_u8 v1, v1
	ds_read_b128 v[172:175], v2
	ds_read_b128 v[168:171], v2 offset:1024
	ds_read_b128 v[164:167], v2 offset:2048
	ds_read_b128 v[160:163], v2 offset:3072
	ds_read_b128 v[156:159], v2 offset:4096
	ds_read_b128 v[152:155], v2 offset:5120
	ds_read_b128 v[148:151], v2 offset:6144
	ds_read_b128 v[144:147], v2 offset:7168
	s_waitcnt lgkmcnt(8)
	v_bitop3_b32 v3, v1, v205, 15 bitop3:0x6c
	v_lshlrev_b32_e32 v3, 4, v3
	v_lshlrev_b32_e32 v132, 8, v1
	v_add3_u32 v249, 0, v3, v132
	v_bitop3_b32 v3, v1, v207, 15 bitop3:0x6c
	v_lshlrev_b32_e32 v3, 4, v3
	v_lshl_add_u32 v1, v1, 2, 0
	v_add3_u32 v248, 0, v3, v132
	v_add_u32_e32 v246, 0x10000, v1
	ds_read_b128 v[140:143], v249
	ds_read_b128 v[132:135], v248
	ds_read_b32 v247, v246
	v_mov_b32_e32 v136, 0
	v_mov_b32_e32 v137, 0
	v_mov_b32_e32 v138, 0
	v_mov_b32_e32 v139, 0
	v_mov_b32_e32 v1, v0
	v_mov_b32_e32 v2, v0
	v_mov_b32_e32 v3, v0
	s_andn2_b64 vcc, exec, s[44:45]
	s_cbranch_vccnz .Lpvil_dh1
	s_cmp_eq_u32 s99, 0
	s_cbranch_scc1 .Lpvil_o0
	s_waitcnt lgkmcnt(10)
	v_mfma_f32_16x16x32_bf16 v[176:179], v[96:99], v[172:175], 0
	v_mfma_f32_16x16x32_bf16 v[180:183], v[100:103], v[172:175], 0
	v_mfma_f32_16x16x32_bf16 v[136:139], v[0:3], v[172:175], 0
	global_load_dwordx4 v[32:35], v[252:253], off
	global_load_dwordx4 v[40:43], v[252:253], off offset:1024
	s_waitcnt lgkmcnt(9)
	v_mfma_f32_16x16x32_bf16 v[172:175], v[92:95], v[168:171], v[176:179]
	v_mfma_f32_16x16x32_bf16 v[176:179], v[104:107], v[168:171], v[180:183]
	v_mfma_f32_16x16x32_bf16 v[136:139], v[0:3], v[168:171], v[136:139]
	global_load_dwordx4 v[44:47], v[252:253], off offset:2048
	global_load_dwordx4 v[48:51], v[252:253], off offset:3072
	s_waitcnt lgkmcnt(8)
	v_mfma_f32_16x16x32_bf16 v[168:171], v[88:91], v[164:167], v[172:175]
	v_mfma_f32_16x16x32_bf16 v[172:175], v[108:111], v[164:167], v[176:179]
	v_mfma_f32_16x16x32_bf16 v[136:139], v[0:3], v[164:167], v[136:139]
	v_lshl_add_u64 v[254:255], v[252:253], 0, s[100:101]
	global_load_dwordx4 v[52:55], v[254:255], off
	global_load_dwordx4 v[56:59], v[254:255], off offset:1024
	s_waitcnt lgkmcnt(7)
	v_mfma_f32_16x16x32_bf16 v[164:167], v[84:87], v[160:163], v[168:171]
	v_mfma_f32_16x16x32_bf16 v[168:171], v[112:115], v[160:163], v[172:175]
	v_mfma_f32_16x16x32_bf16 v[136:139], v[0:3], v[160:163], v[136:139]
	global_load_dwordx4 v[60:63], v[254:255], off offset:2048
	global_load_dwordx4 v[64:67], v[254:255], off offset:3072
	s_waitcnt lgkmcnt(6)
	v_mfma_f32_16x16x32_bf16 v[160:163], v[80:83], v[156:159], v[164:167]
	v_mfma_f32_16x16x32_bf16 v[164:167], v[116:119], v[156:159], v[168:171]
	v_mfma_f32_16x16x32_bf16 v[136:139], v[0:3], v[156:159], v[136:139]
	v_lshl_add_u64 v[254:255], v[254:255], 0, s[100:101]
	global_load_dwordx4 v[36:39], v[254:255], off
	global_load_dwordx4 v[28:31], v[254:255], off offset:1024
	s_waitcnt lgkmcnt(5)
	v_mfma_f32_16x16x32_bf16 v[156:159], v[76:79], v[152:155], v[160:163]
	v_mfma_f32_16x16x32_bf16 v[160:163], v[120:123], v[152:155], v[164:167]
	v_mfma_f32_16x16x32_bf16 v[136:139], v[0:3], v[152:155], v[136:139]
	global_load_dwordx4 v[24:27], v[254:255], off offset:2048
	global_load_dwordx4 v[20:23], v[254:255], off offset:3072
	s_waitcnt lgkmcnt(4)
	v_mfma_f32_16x16x32_bf16 v[152:155], v[72:75], v[148:151], v[156:159]
	v_mfma_f32_16x16x32_bf16 v[156:159], v[124:127], v[148:151], v[160:163]
	v_mfma_f32_16x16x32_bf16 v[136:139], v[0:3], v[148:151], v[136:139]
	v_lshl_add_u64 v[254:255], v[254:255], 0, s[100:101]
	global_load_dwordx4 v[16:19], v[254:255], off
	global_load_dwordx4 v[12:15], v[254:255], off offset:1024
	s_waitcnt lgkmcnt(3)
	v_mfma_f32_16x16x32_bf16 v[152:155], v[68:71], v[144:147], v[152:155]
	v_mfma_f32_16x16x32_bf16 v[148:151], v[128:131], v[144:147], v[156:159]
	v_mfma_f32_16x16x32_bf16 v[136:139], v[0:3], v[144:147], v[136:139]
	global_load_dwordx4 v[8:11], v[254:255], off offset:2048
	global_load_dwordx4 v[4:7], v[254:255], off offset:3072
	s_mov_b32 s99, 0
	s_branch .Lpvil_tail
; #define MFMA16(a, b, c) __builtin_amdgcn_mfma_f32_16x16x32_bf16((a), (b), (c), 0, 0, 0)
;     ...
;               for (int ks = 0; ks < 8; ++ks) {
;                 const bf16x8 pb = __builtin_bit_cast(bf16x8, pw[ks]);
;                 o0 = MFMA16(vf[0][ks], pb, o0); o1 = MFMA16(vf[1][ks], pb, o1);
;                 if (dh == 0) ol = MFMA16(ones, pb, ol);
;               }
;               if (qv) {
;                 *op0 = a0 + o0; *op1 = a1 + o1;
;                 if (dh == 0 && fq == 0) lsl[qidx] = al + ol[0];
;               }
;             }
.Lpvil_o0:
	s_waitcnt lgkmcnt(10)
	v_mfma_f32_16x16x32_bf16 v[176:179], v[96:99], v[172:175], 0
	v_mfma_f32_16x16x32_bf16 v[180:183], v[100:103], v[172:175], 0
	v_mfma_f32_16x16x32_bf16 v[136:139], v[0:3], v[172:175], 0
	s_waitcnt lgkmcnt(9)
	v_mfma_f32_16x16x32_bf16 v[172:175], v[92:95], v[168:171], v[176:179]
	v_mfma_f32_16x16x32_bf16 v[176:179], v[104:107], v[168:171], v[180:183]
	v_mfma_f32_16x16x32_bf16 v[136:139], v[0:3], v[168:171], v[136:139]
	s_waitcnt lgkmcnt(8)
	v_mfma_f32_16x16x32_bf16 v[168:171], v[88:91], v[164:167], v[172:175]
	v_mfma_f32_16x16x32_bf16 v[172:175], v[108:111], v[164:167], v[176:179]
	v_mfma_f32_16x16x32_bf16 v[136:139], v[0:3], v[164:167], v[136:139]
	s_waitcnt lgkmcnt(7)
	v_mfma_f32_16x16x32_bf16 v[164:167], v[84:87], v[160:163], v[168:171]
	v_mfma_f32_16x16x32_bf16 v[168:171], v[112:115], v[160:163], v[172:175]
	v_mfma_f32_16x16x32_bf16 v[136:139], v[0:3], v[160:163], v[136:139]
	s_waitcnt lgkmcnt(6)
	v_mfma_f32_16x16x32_bf16 v[160:163], v[80:83], v[156:159], v[164:167]
	v_mfma_f32_16x16x32_bf16 v[164:167], v[116:119], v[156:159], v[168:171]
	v_mfma_f32_16x16x32_bf16 v[136:139], v[0:3], v[156:159], v[136:139]
	s_waitcnt lgkmcnt(5)
	v_mfma_f32_16x16x32_bf16 v[156:159], v[76:79], v[152:155], v[160:163]
	v_mfma_f32_16x16x32_bf16 v[160:163], v[120:123], v[152:155], v[164:167]
	v_mfma_f32_16x16x32_bf16 v[136:139], v[0:3], v[152:155], v[136:139]
	s_waitcnt lgkmcnt(4)
	v_mfma_f32_16x16x32_bf16 v[152:155], v[72:75], v[148:151], v[156:159]
	v_mfma_f32_16x16x32_bf16 v[156:159], v[124:127], v[148:151], v[160:163]
	v_mfma_f32_16x16x32_bf16 v[136:139], v[0:3], v[148:151], v[136:139]
	s_waitcnt lgkmcnt(3)
	v_mfma_f32_16x16x32_bf16 v[152:155], v[68:71], v[144:147], v[152:155]
	v_mfma_f32_16x16x32_bf16 v[148:151], v[128:131], v[144:147], v[156:159]
	v_mfma_f32_16x16x32_bf16 v[136:139], v[0:3], v[144:147], v[136:139]
	s_branch .Lpvil_tail
.Lpvil_dh1:
	s_cmp_eq_u32 s99, 0
	s_cbranch_scc1 .Lpvil_p0
	s_waitcnt lgkmcnt(10)
	v_mfma_f32_16x16x32_bf16 v[176:179], v[96:99], v[172:175], 0
	v_mfma_f32_16x16x32_bf16 v[180:183], v[100:103], v[172:175], 0
	global_load_dwordx4 v[32:35], v[252:253], off
	global_load_dwordx4 v[40:43], v[252:253], off offset:1024
	s_waitcnt lgkmcnt(9)
	v_mfma_f32_16x16x32_bf16 v[172:175], v[92:95], v[168:171], v[176:179]
	v_mfma_f32_16x16x32_bf16 v[176:179], v[104:107], v[168:171], v[180:183]
	global_load_dwordx4 v[44:47], v[252:253], off offset:2048
	global_load_dwordx4 v[48:51], v[252:253], off offset:3072
	s_waitcnt lgkmcnt(8)
	v_mfma_f32_16x16x32_bf16 v[168:171], v[88:91], v[164:167], v[172:175]
	v_mfma_f32_16x16x32_bf16 v[172:175], v[108:111], v[164:167], v[176:179]
	v_lshl_add_u64 v[254:255], v[252:253], 0, s[100:101]
	global_load_dwordx4 v[52:55], v[254:255], off
	global_load_dwordx4 v[56:59], v[254:255], off offset:1024
	s_waitcnt lgkmcnt(7)
	v_mfma_f32_16x16x32_bf16 v[164:167], v[84:87], v[160:163], v[168:171]
	v_mfma_f32_16x16x32_bf16 v[168:171], v[112:115], v[160:163], v[172:175]
	global_load_dwordx4 v[60:63], v[254:255], off offset:2048
	global_load_dwordx4 v[64:67], v[254:255], off offset:3072
	s_waitcnt lgkmcnt(6)
	v_mfma_f32_16x16x32_bf16 v[160:163], v[80:83], v[156:159], v[164:167]
	v_mfma_f32_16x16x32_bf16 v[164:167], v[116:119], v[156:159], v[168:171]
	v_lshl_add_u64 v[254:255], v[254:255], 0, s[100:101]
	global_load_dwordx4 v[36:39], v[254:255], off
	global_load_dwordx4 v[28:31], v[254:255], off offset:1024
	s_waitcnt lgkmcnt(5)
	v_mfma_f32_16x16x32_bf16 v[156:159], v[76:79], v[152:155], v[160:163]
	v_mfma_f32_16x16x32_bf16 v[160:163], v[120:123], v[152:155], v[164:167]
	global_load_dwordx4 v[24:27], v[254:255], off offset:2048
	global_load_dwordx4 v[20:23], v[254:255], off offset:3072
	s_waitcnt lgkmcnt(4)
	v_mfma_f32_16x16x32_bf16 v[152:155], v[72:75], v[148:151], v[156:159]
	v_mfma_f32_16x16x32_bf16 v[156:159], v[124:127], v[148:151], v[160:163]
	v_lshl_add_u64 v[254:255], v[254:255], 0, s[100:101]
	global_load_dwordx4 v[16:19], v[254:255], off
	global_load_dwordx4 v[12:15], v[254:255], off offset:1024
	s_waitcnt lgkmcnt(3)
	v_mfma_f32_16x16x32_bf16 v[152:155], v[68:71], v[144:147], v[152:155]
	v_mfma_f32_16x16x32_bf16 v[148:151], v[128:131], v[144:147], v[156:159]
	global_load_dwordx4 v[8:11], v[254:255], off offset:2048
	global_load_dwordx4 v[4:7], v[254:255], off offset:3072
	s_mov_b32 s99, 0
	s_branch .Lpvil_tail
.Lpvil_p0:
	s_waitcnt lgkmcnt(10)
	v_mfma_f32_16x16x32_bf16 v[176:179], v[96:99], v[172:175], 0
	v_mfma_f32_16x16x32_bf16 v[180:183], v[100:103], v[172:175], 0
	s_waitcnt lgkmcnt(9)
	v_mfma_f32_16x16x32_bf16 v[172:175], v[92:95], v[168:171], v[176:179]
	v_mfma_f32_16x16x32_bf16 v[176:179], v[104:107], v[168:171], v[180:183]
	s_waitcnt lgkmcnt(8)
	v_mfma_f32_16x16x32_bf16 v[168:171], v[88:91], v[164:167], v[172:175]
	v_mfma_f32_16x16x32_bf16 v[172:175], v[108:111], v[164:167], v[176:179]
	s_waitcnt lgkmcnt(7)
	v_mfma_f32_16x16x32_bf16 v[164:167], v[84:87], v[160:163], v[168:171]
	v_mfma_f32_16x16x32_bf16 v[168:171], v[112:115], v[160:163], v[172:175]
	s_waitcnt lgkmcnt(6)
	v_mfma_f32_16x16x32_bf16 v[160:163], v[80:83], v[156:159], v[164:167]
	v_mfma_f32_16x16x32_bf16 v[164:167], v[116:119], v[156:159], v[168:171]
	s_waitcnt lgkmcnt(5)
	v_mfma_f32_16x16x32_bf16 v[156:159], v[76:79], v[152:155], v[160:163]
	v_mfma_f32_16x16x32_bf16 v[160:163], v[120:123], v[152:155], v[164:167]
	s_waitcnt lgkmcnt(4)
	v_mfma_f32_16x16x32_bf16 v[152:155], v[72:75], v[148:151], v[156:159]
	v_mfma_f32_16x16x32_bf16 v[156:159], v[124:127], v[148:151], v[160:163]
	s_waitcnt lgkmcnt(3)
	v_mfma_f32_16x16x32_bf16 v[152:155], v[68:71], v[144:147], v[152:155]
	v_mfma_f32_16x16x32_bf16 v[148:151], v[128:131], v[144:147], v[156:159]
.Lpvil_tail:
	s_waitcnt lgkmcnt(0)
	s_nop 7
